# v26 + prep phase: task->block mapping rebalanced (the 64 K=2816 weight slabs swapped with 64 K=1024 slabs so no block gets 19 chunks; max 15)
# speedup vs baseline: 1.0058x; 1.0058x over previous
.LBB0_17:
	s_or_b64 exec, exec, s[6:7]
	s_load_dwordx16 s[36:51], s[0:1], 0x40
	v_mov_b32_e32 v72, v213
	s_cmpk_gt_i32 s2, 0x29f
	s_waitcnt lgkmcnt(0)
	v_writelane_b32 v252, s36, 10
	s_nop 1
	v_writelane_b32 v252, s37, 11
	v_writelane_b32 v252, s38, 12
	v_writelane_b32 v252, s39, 13
	v_writelane_b32 v252, s40, 14
	v_writelane_b32 v252, s41, 15
	v_writelane_b32 v252, s42, 16
	v_writelane_b32 v252, s43, 17
	v_writelane_b32 v252, s44, 18
	v_writelane_b32 v252, s45, 19
	v_writelane_b32 v252, s46, 20
	v_writelane_b32 v252, s47, 21
	v_writelane_b32 v252, s48, 22
	v_writelane_b32 v252, s49, 23
	v_writelane_b32 v252, s50, 24
	v_writelane_b32 v252, s51, 25
	s_cbranch_scc1 .LBB0_138
	v_ashrrev_i32_e32 v2, 3, v72
	s_movk_i32 s0, 0x210
	v_writelane_b32 v252, s4, 26
	v_mul_lo_u32 v5, v2, s0
	s_movk_i32 s0, 0x80
	v_writelane_b32 v252, s5, 27
	v_cmp_gt_i32_e64 s[6:7], s0, v72
	s_add_u32 s0, s24, 0x4c00000
	v_writelane_b32 v252, s0, 28
	s_addc_u32 s0, s25, 0
	s_add_u32 s88, s24, 0x2000000
	s_addc_u32 s89, s25, 0
	s_add_u32 s90, s24, 0x6218000
	s_addc_u32 s91, s25, 0
	s_add_u32 s92, s24, 0x622e000
	s_addc_u32 s93, s25, 0
	s_add_u32 s94, s24, 0x1c00000
	s_addc_u32 s95, s25, 0
	s_add_u32 s3, s24, 0x1400000
	s_addc_u32 s33, s25, 0
	s_mov_b32 s5, s52
	s_add_u32 s52, s24, 0x6210000
	s_addc_u32 s4, s25, 0
	s_add_u32 s54, s24, 0x6214000
	s_addc_u32 s55, s25, 0
	s_add_u32 s56, s24, 0x1000000
	s_addc_u32 s57, s25, 0
	s_add_u32 s58, s82, 0x1000
	s_addc_u32 s59, s83, 0
	v_writelane_b32 v252, s0, 30
	s_add_u32 s60, s84, 0x1000
	s_addc_u32 s61, s85, 0
	v_writelane_b32 v252, s72, 32
	v_ashrrev_i32_e32 v74, 4, v72
	v_ashrrev_i32_e32 v75, 31, v74
	v_writelane_b32 v252, s73, 33
	v_writelane_b32 v252, s74, 34
	v_writelane_b32 v252, s75, 35
	v_writelane_b32 v252, s76, 36
	v_writelane_b32 v252, s77, 37
	v_writelane_b32 v252, s78, 38
	v_writelane_b32 v252, s79, 39
	v_lshlrev_b32_e32 v0, 2, v72
	v_lshlrev_b64 v[92:93], 2, v[74:75]
	s_mov_b64 s[10:11], 0x780
	v_writelane_b32 v252, s80, 40
	v_and_b32_e32 v0, 60, v0
	v_lshl_add_u64 v[100:101], v[92:93], 0, s[10:11]
	s_mov_b64 s[10:11], 0x400
	v_writelane_b32 v252, s81, 41
	v_lshlrev_b32_e32 v6, 8, v74
	v_lshlrev_b32_e32 v7, 2, v0
	v_lshl_add_u64 v[102:103], v[92:93], 0, s[10:11]
	s_mov_b64 s[10:11], 0x700
	v_writelane_b32 v252, s82, 42
	v_add3_u32 v91, 0, v6, v7
	v_lshlrev_b32_e32 v7, 4, v72
	v_lshl_add_u64 v[104:105], v[92:93], 0, s[10:11]
	s_mov_b64 s[10:11], 0x480
	v_writelane_b32 v252, s83, 43
	v_and_b32_e32 v8, 0x70, v7
	s_add_u32 s62, s24, 0x6200000
	v_lshl_add_u64 v[106:107], v[92:93], 0, s[10:11]
	s_mov_b64 s[10:11], 0x680
	v_writelane_b32 v252, s84, 44
	v_lshlrev_b32_e32 v3, 2, v2
	v_lshrrev_b32_e32 v4, 1, v2
	v_and_b32_e32 v117, 63, v72
	v_add3_u32 v119, 0, v5, v8
	v_lshlrev_b32_e32 v8, 7, v72
	s_addc_u32 s63, s25, 0
	v_lshl_add_u64 v[108:109], v[92:93], 0, s[10:11]
	s_mov_b64 s[10:11], 0x500
	v_writelane_b32 v252, s85, 45
	v_mov_b32_e32 v77, 0
	v_lshl_add_u32 v1, v74, 1, 0
	v_and_b32_e32 v3, 16, v3
	v_and_b32_e32 v4, 12, v4
	v_and_b32_e32 v2, 35, v2
	v_lshl_add_u32 v6, v117, 2, 0
	v_add_u32_e32 v78, 32, v74
	v_add_u32_e32 v80, 64, v74
	v_add_u32_e32 v82, 0x60, v74
	v_add_u32_e32 v84, 0x80, v74
	v_add_u32_e32 v86, 0xa0, v74
	v_add_u32_e32 v88, 0xc0, v74
	v_add_u32_e32 v90, 0xe0, v74
	v_mul_u32_u24_e32 v5, 0x210, v0
	v_and_b32_e32 v8, 0xffffe000, v8
	s_add_u32 s64, s24, 0x6208000
	v_and_b32_e32 v9, 7, v72
	v_mov_b32_e32 v10, 0x100
	v_and_b32_e32 v96, 0xf0, v7
	v_lshl_add_u64 v[110:111], v[92:93], 0, s[10:11]
	s_mov_b64 s[10:11], 0x600
	s_mov_b64 s[12:13], 0x580
	v_writelane_b32 v252, s86, 46
	s_mov_b32 s1, 0
	v_cmp_gt_u32_e64 s[8:9], 64, v72
	v_ashrrev_i32_e32 v73, 31, v78
	v_ashrrev_i32_e32 v79, 31, v80
	v_ashrrev_i32_e32 v81, 31, v82
	v_ashrrev_i32_e32 v83, 31, v84
	v_ashrrev_i32_e32 v85, 31, v86
	v_ashrrev_i32_e32 v87, 31, v88
	v_ashrrev_i32_e32 v89, 31, v90
	s_addc_u32 s65, s25, 0
	v_lshl_or_b32 v94, v9, 4, v10
	v_mov_b32_e32 v95, v77
	v_or3_b32 v121, v2, v3, v4
	v_mov_b32_e32 v97, v77
	v_or_b32_e32 v98, 8, v96
	v_mov_b32_e32 v99, v77
	v_lshlrev_b32_e32 v76, 2, v0
	v_add_u32_e32 v123, v1, v5
	v_add_u32_e32 v125, v6, v8
	s_movk_i32 s66, 0x7fff
	s_mov_b32 s67, s2
	s_mov_b32 s100, s2
	v_mov_b32_e32 v127, 1
	v_lshl_add_u64 v[112:113], v[92:93], 0, s[10:11]
	v_lshl_add_u64 v[114:115], v[92:93], 0, s[12:13]
	v_writelane_b32 v252, s87, 47
	s_branch .LBB0_21

.LBB0_20:
	s_add_i32 s100, s100, s26
	s_cmpk_gt_i32 s100, 0x29f
	s_cbranch_scc1 .LBB0_137
.LBB0_21:
	s_mov_b32 s67, s100
	s_sub_u32 s101, s100, 0x1c0
	s_cmp_lt_u32 s101, 64
	s_cbranch_scc0 .Lprep_rm1
	s_add_i32 s67, s100, 0xa0
.Lprep_rm1:
	s_sub_u32 s101, s100, 0x260
	s_cmp_lt_u32 s101, 64
	s_cbranch_scc0 .Lprep_rm2
	s_sub_i32 s67, s100, 0xa0
